# barrier relocation + static s_setprio 1 for waves 0-3 inside the flash-attention units
# baseline (speedup 1.0000x reference)
; #define QLOOP2(qi_, r2_, n_, ...) for (;;) { if (tid == 0) s_item = (int)atomicAdd(ctr + 64 * (qi_) + 32 * (r2_), 1u); __syncthreads(); const int item = s_item; __syncthreads(); if (item >= (n_)) break; __VA_ARGS__ }
; template <int PHM, int MIXM>
; __global__ void __launch_bounds__(512, 2) mega(Args Aval) {
;     ...
;             for (int r2 = 0; r2 < ((PROBE_DUP & 16) ? 2 : 1); ++r2) if (MIXM & 1) QLOOP2(0, r2, 256, { const int L = 15 - (item >> 4), r = item & 15; flash_unit<0>(A, l, r >> 2, r & 3, L, lds); })
.LBB0_735:
	s_or_b64 exec, exec, s[2:3]
	s_waitcnt vmcnt(0) lgkmcnt(0)
	s_barrier
	ds_read_b32 v0, v177 offset:8
	s_mov_b64 s[2:3], -1
	s_waitcnt lgkmcnt(0)
	s_barrier
	v_cmp_gt_i32_e32 vcc, s68, v0
	v_readfirstlane_b32 s4, v0
	s_cbranch_vccz .LBB0_730
	v_readfirstlane_b32 s100, v238
	s_cmp_ge_u32 s100, 0x100
	s_cbranch_scc1 .Lprio_skip_mla
	s_setprio 1

; #define QLOOP2(qi_, r2_, n_, ...) for (;;) { if (tid == 0) s_item = (int)atomicAdd(ctr + 64 * (qi_) + 32 * (r2_), 1u); __syncthreads(); const int item = s_item; __syncthreads(); if (item >= (n_)) break; __VA_ARGS__ }
; template <int PHM, int MIXM>
; __global__ void __launch_bounds__(512, 2) mega(Args Aval) {
;     ...
;             for (int r2 = 0; r2 < ((PROBE_DUP & 16) ? 2 : 1); ++r2) if (MIXM & 1) QLOOP2(0, r2, 256, { const int L = 15 - (item >> 4), r = item & 15; flash_unit<0>(A, l, r >> 2, r & 3, L, lds); })
;             for (int r2 = 0; r2 < ((PROBE_DUP & 32) ? 2 : 1); ++r2) if (MIXM & 2) QLOOP2(1, r2, 256, { const int L = 15 - (item >> 4), r = item & 15; flash_unit<2>(A, l, r >> 2, r & 3, L, lds); })
.LBB0_765:
	s_or_b64 exec, exec, s[2:3]
	s_waitcnt lgkmcnt(0)
	s_barrier
	ds_read_b32 v0, v177 offset:8
	s_mov_b64 s[2:3], -1
	s_waitcnt lgkmcnt(0)
	s_barrier
	v_cmp_gt_i32_e32 vcc, s68, v0
	v_readfirstlane_b32 s5, v0
	s_cbranch_vccz .LBB0_760
	v_readfirstlane_b32 s100, v238
	s_cmp_ge_u32 s100, 0x100
	s_cbranch_scc1 .Lprio_skip_ret
	s_setprio 1

; #define QLOOP2(qi_, r2_, n_, ...) for (;;) { if (tid == 0) s_item = (int)atomicAdd(ctr + 64 * (qi_) + 32 * (r2_), 1u); __syncthreads(); const int item = s_item; __syncthreads(); if (item >= (n_)) break; __VA_ARGS__ }
; template <int PHM, int MIXM>
; __global__ void __launch_bounds__(512, 2) mega(Args Aval) {
;     ...
;             for (int r2 = 0; r2 < ((PROBE_DUP & 16) ? 2 : 1); ++r2) if (MIXM & 1) QLOOP2(0, r2, 256, { const int L = 15 - (item >> 4), r = item & 15; flash_unit<0>(A, l, r >> 2, r & 3, L, lds); })
;             for (int r2 = 0; r2 < ((PROBE_DUP & 32) ? 2 : 1); ++r2) if (MIXM & 2) QLOOP2(1, r2, 256, { const int L = 15 - (item >> 4), r = item & 15; flash_unit<2>(A, l, r >> 2, r & 3, L, lds); })
;             for (int r2 = 0; r2 < ((PROBE_DUP & 64) ? 2 : 1); ++r2) if (MIXM & 8) QLOOP2(2, r2, 256, { s5_unit(A, l, item, lds, wave, lane); })
;             for (int r2 = 0; r2 < ((PROBE_DUP & 128) ? 2 : 1); ++r2) if (MIXM & 4) QLOOP2(3, r2, 512, { const int L = 31 - (item >> 4), r = item & 15; flash_unit<1>(A, l, r >> 2, r & 3, L, lds); })
.LBB0_801:
	s_or_b64 exec, exec, s[2:3]
	s_waitcnt lgkmcnt(0)
	s_barrier
	ds_read_b32 v0, v177 offset:8
	s_movk_i32 s2, 0x1ff
	s_waitcnt lgkmcnt(0)
	s_barrier
	v_cmp_lt_i32_e32 vcc, s2, v0
	v_readfirstlane_b32 s4, v0
	s_mov_b64 s[2:3], -1
	s_cbranch_vccnz .LBB0_796
	v_readfirstlane_b32 s100, v238
	s_cmp_ge_u32 s100, 0x100
	s_cbranch_scc1 .Lprio_skip_diff
	s_setprio 1
